# tile barrier moved to mid-iteration in both attention loops (staging writes earlier, no barrier at loop end)
# speedup vs baseline: 1.1091x; 1.0199x over previous
; #define SBAR() __builtin_amdgcn_sched_barrier(0)
; #define SWRITED(boff) do { char* bb_ = lds + (boff); *reinterpret_cast<bf16x8*>(bb_ + KN_OFF + kn_st) = s_kn; *reinterpret_cast<bf16x8*>(bb_ + V_OFF + vst0) = s_v0; \
;     *reinterpret_cast<bf16x8*>(bb_ + V_OFF + vst1) = s_v1; if (tid < 64) *reinterpret_cast<float*>(bb_ + PK_OFF + tid * 4) = s_pk; } while (0)
; #define VRD(D0, L, H) do { constexpr int KS = 2 * 4 * 512, HF = 4 * 512, B0 = (D0) * 512; \
;             L[0] = tr_read<B0>(vb); H[0] = tr_read<B0 + HF>(vb); L[1] = tr_read<B0 + KS>(vb); H[1] = tr_read<B0 + KS + HF>(vb); \
;             L[2] = tr_read<B0 + 2 * KS>(vb); H[2] = tr_read<B0 + 2 * KS + HF>(vb); L[3] = tr_read<B0 + 3 * KS>(vb); H[3] = tr_read<B0 + 3 * KS + HF>(vb); } while (0)
; #define PVM(D0, L, H) do { o[D0] = __builtin_amdgcn_mfma_f32_32x32x16_bf16(fa0, VFR(L, H, 0), o[D0], 0, 0, 0); o[D0] = __builtin_amdgcn_mfma_f32_32x32x16_bf16(fa1, VFR(L, H, 1), o[D0], 0, 0, 0); \
;             o[D0] = __builtin_amdgcn_mfma_f32_32x32x16_bf16(fa2, VFR(L, H, 2), o[D0], 0, 0, 0); o[D0] = __builtin_amdgcn_mfma_f32_32x32x16_bf16(fa3, VFR(L, H, 3), o[D0], 0, 0, 0); } while (0)
; __device__ __forceinline__ void attn_diff1(const bf16* __restrict__ Qrow, const bf16* __restrict__ Kn, const bf16* __restrict__ Vh, const int* __restrict__ posk, const float pq, const float cneg, ...
;     ...
;         VRD(3, lb, hb);
;         asm volatile("s_waitcnt lgkmcnt(8)" ::: "memory"); SBAR();
;         PVM(2, la, ha);
;         asm volatile("s_waitcnt lgkmcnt(0)" ::: "memory"); SBAR();
;         PVM(3, lb, hb);
;     ...
;         if (t + 1 < NT) SWRITED(BUF - cur);
;         __syncthreads();
;         cur = BUF - cur;
;     }
.Ld1_nostage:
	s_waitcnt lgkmcnt(0)
	s_barrier
	v_mfma_f32_32x32x16_bf16 v[48:63], v[84:87], v[140:143], v[48:63]
	v_mfma_f32_32x32x16_bf16 v[32:47], v[84:87], v[144:147], v[32:47]
	v_mfma_f32_32x32x16_bf16 v[16:31], v[84:87], v[148:151], v[16:31]
	v_mfma_f32_32x32x16_bf16 v[0:15], v[84:87], v[152:155], v[0:15]
	s_sub_i32 s45, 0x7900, s45
	s_add_i32 s69, s69, 1
	v_add_u32_e32 v206, 64, v206
	v_add_u32_e32 v208, 64, v208
	v_add_u32_e32 v210, 64, v210
	s_cmp_eq_u32 s54, s69
	s_cbranch_scc1 .LBB0_537
	s_branch .LBB0_531

; #define SBAR() __builtin_amdgcn_sched_barrier(0)
; #define SLOAD2(k0) do { s_kn = *reinterpret_cast<const bf16x8*>(Kn + (size_t)((k0) + kn_r) * 1024 + kn_c); s_kr = *reinterpret_cast<const bf16x8*>(Kr + (size_t)((k0) + kr_r) * 32 + kr_c); \
;     s_v = *reinterpret_cast<const bf16x8*>(Vh + (size_t)((k0) + kn_r) * 1024 + kn_c); } while (0)
; __device__ __forceinline__ void attn_mla2(const bf16* __restrict__ Q0, const bf16* __restrict__ Q1, const bf16* __restrict__ Kn, const bf16* __restrict__ Kr, const bf16* __restrict__ Vh, ...
;     ...
;     for (int t = 0; t < NT; ++t) {
;         const char* buf = lds + cur;
;         f32x16 pa0 = f32x16{}, pa1 = f32x16{}, pb0 = f32x16{}, pb1 = f32x16{};
;         {
;             const char* kb = buf + KN_OFF + r32 * 144 + hi * 16; const char* kr = buf + KR_OFF + r32 * 80 + hi * 16;
;     ...
;             bf16x8 c0 = KLD0(0), c1 = KLD1(0);
; #pragma unroll
;             for (int d0 = 0; d0 < 6; ++d0) {
;                 bf16x8 n0 = c0, n1 = c1;
;                 if (d0 + 1 < 6) { n0 = KLD0(d0 + 1); n1 = KLD1(d0 + 1); }
;                 pa0 = __builtin_amdgcn_mfma_f32_32x32x16_bf16(c0, q0[d0], pa0, 0, 0, 0); pb0 = __builtin_amdgcn_mfma_f32_32x32x16_bf16(c0, q1[d0], pb0, 0, 0, 0);
;                 pa1 = __builtin_amdgcn_mfma_f32_32x32x16_bf16(c1, q0[d0], pa1, 0, 0, 0); pb1 = __builtin_amdgcn_mfma_f32_32x32x16_bf16(c1, q1[d0], pb1, 0, 0, 0);
;                 SBAR(); c0 = n0; c1 = n1;
;             }
;     ...
;         }
;         if (t + 1 < NT) SLOAD2((t + 1) * 64);
;         bf16x8 fa0, fa1, fa2, fa3, fb0, fb1, fb2, fb3;
;         {   float ps = 0.f;
; #pragma unroll
;             for (int r = 0; r < 16; ++r) { pa0[r] = __builtin_amdgcn_exp2f(pa0[r]); pa1[r] = __builtin_amdgcn_exp2f(pa1[r]);     ps += pa0[r] + pa1[r]; }
;             l0 += ps; PK4(pa0, 0, fa0); PK4(pa0, 8, fa1); PK4(pa1, 0, fa2); PK4(pa1, 8, fa3); }
;         {   float ps = 0.f;
; #pragma unroll
;             for (int r = 0; r < 16; ++r) { pb0[r] = __builtin_amdgcn_exp2f(pb0[r]); pb1[r] = __builtin_amdgcn_exp2f(pb1[r]); ps += pb0[r] + pb1[r]; }
;             l1 += ps; PK4(pb0, 0, fb0); PK4(pb0, 8, fb1); PK4(pb1, 0, fb2); PK4(pb1, 8, fb3); }
.LBB0_1629:
	s_add_i32 s12, s16, 0
	v_add3_u32 v184, s12, v246, v244
	v_add3_u32 v188, s12, v245, v244
	ds_read_b128 v[196:199], v184
	ds_read_b128 v[200:203], v184 offset:32
	ds_read_b128 v[204:207], v184 offset:64
	ds_read_b128 v[208:211], v184 offset:96
	ds_read_b128 v[212:215], v188 offset:9216
	ds_read_b128 v[216:219], v188 offset:9248
	ds_read_b128 v[220:223], v184 offset:4608
	ds_read_b128 v[224:227], v184 offset:4640
	ds_read_b128 v[228:231], v184 offset:4672
	ds_read_b128 v[232:235], v184 offset:4704
	ds_read_b128 v[236:239], v188 offset:11776
	ds_read_b128 v[250:253], v188 offset:11808
	v_lshl_add_u64 v[176:177], v[194:195], 0, s[2:3]
	s_mov_b32 s12, 0x8e20000
	v_add_co_u32_e32 v178, vcc, s12, v176
	s_mov_b32 s12, 0xae20000
	s_nop 0
	v_addc_co_u32_e32 v179, vcc, 0, v177, vcc
	v_add_co_u32_e32 v176, vcc, s12, v176
	s_nop 1
	v_addc_co_u32_e32 v177, vcc, 0, v177, vcc
	global_load_dwordx4 v[180:183], v[178:179], off
	global_load_dwordx4 v[176:179], v[176:177], off
	v_lshl_add_u64 v[186:187], v[192:193], 0, s[2:3]
	global_load_dwordx2 v[186:187], v[186:187], off
	s_waitcnt lgkmcnt(11)
	v_mfma_f32_32x32x16_bf16 v[96:111], v[196:199], v[160:163], 0
	s_sub_i32 s15, 0, s16
	v_ashrrev_i32_e32 v80, 3, v241
	v_and_b32_e32 v81, 7, v241
	s_waitcnt lgkmcnt(10)
	v_mfma_f32_32x32x16_bf16 v[96:111], v[200:203], v[168:171], v[96:111]
	v_lshlrev_b32_e32 v82, 4, v81
	v_mul_u32_u24_e32 v184, 0x90, v80
	v_add3_u32 v184, s15, v184, v82
	s_waitcnt lgkmcnt(9)
	v_mfma_f32_32x32x16_bf16 v[96:111], v[204:207], v[156:159], v[96:111]
	v_mul_u32_u24_e32 v189, 0x50, v80
	v_lshlrev_b32_e32 v83, 3, v81
	v_add3_u32 v189, s15, v189, v83
	s_waitcnt lgkmcnt(8)
	v_mfma_f32_32x32x16_bf16 v[96:111], v[208:211], v[144:147], v[96:111]
	v_bfe_u32 v83, v241, 3, 2
	v_and_b32_e32 v82, 48, v82
	v_lshlrev_b32_e32 v84, 1, v80
	s_waitcnt lgkmcnt(7)
	v_mfma_f32_32x32x16_bf16 v[96:111], v[212:215], v[140:143], v[96:111]
	v_and_b32_e32 v85, 0x1fffff0, v80
	v_and_b32_e32 v84, 8, v84
	v_or3_b32 v81, v84, v85, v81
	s_waitcnt lgkmcnt(6)
	v_mfma_f32_32x32x16_bf16 v[96:111], v[216:219], v[128:131], v[96:111]
	v_lshrrev_b32_e32 v80, 1, v80
	v_lshlrev_b32_e32 v81, 7, v81
	v_and_b32_e32 v81, 0xfffffe00, v81
	v_and_or_b32 v83, v80, 4, v83
	v_lshlrev_b32_e32 v83, 6, v83
	v_mfma_f32_32x32x16_bf16 v[64:79], v[196:199], v[164:167], 0
	v_add_u32_e32 v80, s15, v81
	v_add3_u32 v188, v80, v83, v82
	v_lshl_add_u64 v[192:193], v[192:193], 0, s[30:31]
	v_lshl_add_u64 v[194:195], v[194:195], 0, s[36:37]
	s_nop 0
	v_mfma_f32_32x32x16_bf16 v[64:79], v[200:203], v[172:175], v[64:79]
	v_exp_f32_e32 v96, v96
	v_exp_f32_e32 v97, v97
	v_add_f32_e32 v190, v190, v96
	v_exp_f32_e32 v98, v98
	v_add_f32_e32 v190, v190, v97
	v_mfma_f32_32x32x16_bf16 v[64:79], v[204:207], v[152:155], v[64:79]
	v_exp_f32_e32 v99, v99
	v_add_f32_e32 v190, v190, v98
	v_exp_f32_e32 v100, v100
	v_add_f32_e32 v190, v190, v99
	v_exp_f32_e32 v101, v101
	v_mfma_f32_32x32x16_bf16 v[64:79], v[208:211], v[148:151], v[64:79]
	v_add_f32_e32 v190, v190, v100
	v_exp_f32_e32 v102, v102
	v_add_f32_e32 v190, v190, v101
	v_exp_f32_e32 v103, v103
	v_add_f32_e32 v190, v190, v102
	v_exp_f32_e32 v104, v104
	v_mfma_f32_32x32x16_bf16 v[64:79], v[212:215], v[136:139], v[64:79]
	v_add_f32_e32 v190, v190, v103
	v_exp_f32_e32 v105, v105
	v_add_f32_e32 v190, v190, v104
	v_exp_f32_e32 v106, v106
	v_add_f32_e32 v190, v190, v105
	v_mfma_f32_32x32x16_bf16 v[64:79], v[216:219], v[132:135], v[64:79]
	v_exp_f32_e32 v107, v107
	v_add_f32_e32 v190, v190, v106
	v_exp_f32_e32 v108, v108
	v_add_f32_e32 v190, v190, v107
	v_exp_f32_e32 v109, v109
	v_and_b32_e32 v213, 32, v241
	v_mad_u32_u24 v212, v213, 24, v248
	v_add_u32_e32 v212, s16, v212
	s_waitcnt lgkmcnt(5)
	v_mfma_f32_32x32x16_bf16 v[112:127], v[220:223], v[160:163], 0
	v_add_f32_e32 v190, v190, v108
	v_exp_f32_e32 v110, v110
	v_add_f32_e32 v190, v190, v109
	v_exp_f32_e32 v111, v111
	v_add_f32_e32 v190, v190, v110
	v_add_f32_e32 v190, v190, v111
	s_waitcnt lgkmcnt(4)
	v_mfma_f32_32x32x16_bf16 v[112:127], v[224:227], v[168:171], v[112:127]
	v_exp_f32_e32 v64, v64
	v_exp_f32_e32 v65, v65
	v_add_f32_e32 v191, v191, v64
	v_exp_f32_e32 v66, v66
	v_add_f32_e32 v191, v191, v65
	s_waitcnt lgkmcnt(3)
	v_mfma_f32_32x32x16_bf16 v[112:127], v[228:231], v[156:159], v[112:127]
	v_exp_f32_e32 v67, v67
	v_add_f32_e32 v191, v191, v66
	v_exp_f32_e32 v68, v68
	v_add_f32_e32 v191, v191, v67
	v_exp_f32_e32 v69, v69
	s_waitcnt lgkmcnt(2)
	v_mfma_f32_32x32x16_bf16 v[112:127], v[232:235], v[144:147], v[112:127]
	v_add_f32_e32 v191, v191, v68
	v_exp_f32_e32 v70, v70
	v_add_f32_e32 v191, v191, v69
	v_exp_f32_e32 v71, v71
	v_add_f32_e32 v191, v191, v70
	v_exp_f32_e32 v72, v72
	s_waitcnt lgkmcnt(1)
	v_mfma_f32_32x32x16_bf16 v[112:127], v[236:239], v[140:143], v[112:127]
	v_add_f32_e32 v191, v191, v71
	v_exp_f32_e32 v73, v73
	v_add_f32_e32 v191, v191, v72
	v_exp_f32_e32 v74, v74
	v_add_f32_e32 v191, v191, v73
	s_waitcnt lgkmcnt(0)
; template <int DVB> __device__ __forceinline__ int v_st(int k, int c) { const int kk = (k & ~0xC) | ((k & 4) << 1) | ((k & 8) >> 1); return ((kk >> 3) * DVB + (c >> 5)) * 512 + ((kk & 7) * 32 + (c & 31)) * 2; }
; __device__ __forceinline__ void attn_mla2(const bf16* __restrict__ Q0, const bf16* __restrict__ Q1, const bf16* __restrict__ Kn, const bf16* __restrict__ Kr, const bf16* __restrict__ Vh, ...
;     ...
;         {   float ps = 0.f;
; #pragma unroll
;             for (int r = 0; r < 16; ++r) { pa0[r] = __builtin_amdgcn_exp2f(pa0[r]); pa1[r] = __builtin_amdgcn_exp2f(pa1[r]);     ps += pa0[r] + pa1[r]; }
;             l0 += ps; PK4(pa0, 0, fa0); PK4(pa0, 8, fa1); PK4(pa1, 0, fa2); PK4(pa1, 8, fa3); }
;         {   float ps = 0.f;
; #pragma unroll
;             for (int r = 0; r < 16; ++r) { pb0[r] = __builtin_amdgcn_exp2f(pb0[r]); pb1[r] = __builtin_amdgcn_exp2f(pb1[r]); ps += pb0[r] + pb1[r]; }
;             l1 += ps; PK4(pb0, 0, fb0); PK4(pb0, 8, fb1); PK4(pb1, 0, fb2); PK4(pb1, 8, fb3); }
;         {   const int vb = vb0 + cur;
;     ...
;             PV2(0); PV2(1);
;     ...
;         }
;         if (t + 1 < NT) {
;             int tw = tid; asm volatile("" : "+v"(tw));
;             char* bb_ = lds + (BUF - cur);
;             *reinterpret_cast<bf16x8*>(bb_ + KN_OFF + (tw >> 3) * 144 + (tw & 7) * 16) = s_kn;
;             if (tw < 256) *reinterpret_cast<bf16x8*>(bb_ + KR_OFF + ((tw >> 2) & 63) * 80 + (tw & 3) * 16) = s_kr;
;             *reinterpret_cast<bf16x8*>(bb_ + V_OFF + v_st<2>(tw >> 3, (tw & 7) * 8)) = s_v;
;         }
;         __syncthreads();
;         cur = BUF - cur;
	v_mfma_f32_32x32x16_bf16 v[112:127], v[250:253], v[128:131], v[112:127]
	v_exp_f32_e32 v75, v75
	v_add_f32_e32 v191, v191, v74
	v_exp_f32_e32 v76, v76
	v_add_f32_e32 v191, v191, v75
	v_exp_f32_e32 v77, v77
	v_mfma_f32_32x32x16_bf16 v[80:95], v[220:223], v[164:167], 0
	v_add_f32_e32 v191, v191, v76
	v_exp_f32_e32 v78, v78
	v_add_f32_e32 v191, v191, v77
	v_exp_f32_e32 v79, v79
	v_add_f32_e32 v191, v191, v78
	v_add_f32_e32 v191, v191, v79
	v_mfma_f32_32x32x16_bf16 v[80:95], v[224:227], v[172:175], v[80:95]
	v_cvt_pk_bf16_f32 v196, v96, v97
	v_cvt_pk_bf16_f32 v197, v98, v99
	v_cvt_pk_bf16_f32 v198, v100, v101
	v_cvt_pk_bf16_f32 v199, v102, v103
	v_cvt_pk_bf16_f32 v200, v104, v105
	v_cvt_pk_bf16_f32 v201, v106, v107
	v_cvt_pk_bf16_f32 v202, v108, v109
	v_cvt_pk_bf16_f32 v203, v110, v111
	v_mfma_f32_32x32x16_bf16 v[80:95], v[228:231], v[152:155], v[80:95]
	ds_read_b64_tr_b16 v[96:97], v212 offset:0
	ds_read_b64_tr_b16 v[98:99], v212 offset:256
	ds_read_b64_tr_b16 v[100:101], v212 offset:2048
	ds_read_b64_tr_b16 v[102:103], v212 offset:2304
	ds_read_b64_tr_b16 v[104:105], v212 offset:512
	ds_read_b64_tr_b16 v[106:107], v212 offset:768
	ds_read_b64_tr_b16 v[108:109], v212 offset:2560
	ds_read_b64_tr_b16 v[110:111], v212 offset:2816
	v_mfma_f32_32x32x16_bf16 v[80:95], v[232:235], v[148:151], v[80:95]
	v_cvt_pk_bf16_f32 v204, v64, v65
	v_cvt_pk_bf16_f32 v205, v66, v67
	v_cvt_pk_bf16_f32 v206, v68, v69
	v_cvt_pk_bf16_f32 v207, v70, v71
	v_cvt_pk_bf16_f32 v208, v72, v73
	v_cvt_pk_bf16_f32 v209, v74, v75
	v_cvt_pk_bf16_f32 v210, v76, v77
	v_cvt_pk_bf16_f32 v211, v78, v79
	v_mfma_f32_32x32x16_bf16 v[80:95], v[236:239], v[136:139], v[80:95]
	ds_read_b64_tr_b16 v[64:65], v212 offset:4096
	ds_read_b64_tr_b16 v[66:67], v212 offset:4352
	ds_read_b64_tr_b16 v[68:69], v212 offset:6144
	ds_read_b64_tr_b16 v[70:71], v212 offset:6400
	ds_read_b64_tr_b16 v[72:73], v212 offset:4608
	ds_read_b64_tr_b16 v[74:75], v212 offset:4864
	ds_read_b64_tr_b16 v[76:77], v212 offset:6656
	ds_read_b64_tr_b16 v[78:79], v212 offset:6912
	v_mfma_f32_32x32x16_bf16 v[80:95], v[250:253], v[132:135], v[80:95]
	v_exp_f32_e32 v112, v112
	v_exp_f32_e32 v113, v113
	v_add_f32_e32 v190, v190, v112
	v_exp_f32_e32 v114, v114
	v_add_f32_e32 v190, v190, v113
	s_waitcnt lgkmcnt(8)
	v_mfma_f32_32x32x16_bf16 v[0:15], v[196:199], v[96:99], v[0:15]
	v_exp_f32_e32 v115, v115
	v_add_f32_e32 v190, v190, v114
	v_exp_f32_e32 v116, v116
	v_add_f32_e32 v190, v190, v115
	v_exp_f32_e32 v117, v117
	v_mfma_f32_32x32x16_bf16 v[32:47], v[204:207], v[96:99], v[32:47]
	v_add_f32_e32 v190, v190, v116
	v_exp_f32_e32 v118, v118
	v_add_f32_e32 v190, v190, v117
	v_exp_f32_e32 v119, v119
	v_add_f32_e32 v190, v190, v118
	v_exp_f32_e32 v120, v120
	v_mfma_f32_32x32x16_bf16 v[16:31], v[196:199], v[104:107], v[16:31]
	v_add_f32_e32 v190, v190, v119
	v_exp_f32_e32 v121, v121
	v_add_f32_e32 v190, v190, v120
	v_exp_f32_e32 v122, v122
	v_add_f32_e32 v190, v190, v121
	v_mfma_f32_32x32x16_bf16 v[48:63], v[204:207], v[104:107], v[48:63]
	v_exp_f32_e32 v123, v123
	v_add_f32_e32 v190, v190, v122
	v_exp_f32_e32 v124, v124
	v_add_f32_e32 v190, v190, v123
	v_exp_f32_e32 v125, v125
	v_mfma_f32_32x32x16_bf16 v[0:15], v[200:203], v[100:103], v[0:15]
	v_add_f32_e32 v190, v190, v124
	v_exp_f32_e32 v126, v126
	v_add_f32_e32 v190, v190, v125
	v_exp_f32_e32 v127, v127
	v_add_f32_e32 v190, v190, v126
	v_add_f32_e32 v190, v190, v127
	s_waitcnt vmcnt(0)
	ds_write_b128 v184, v[180:183] offset:30976
	ds_write_b128 v188, v[176:179] offset:45312
	ds_write_b64 v189, v[186:187] offset:40192
	v_mfma_f32_32x32x16_bf16 v[32:47], v[208:211], v[100:103], v[32:47]
	v_cvt_pk_bf16_f32 v220, v112, v113
	v_cvt_pk_bf16_f32 v221, v114, v115
	v_cvt_pk_bf16_f32 v222, v116, v117
	v_cvt_pk_bf16_f32 v223, v118, v119
	v_cvt_pk_bf16_f32 v224, v120, v121
	v_cvt_pk_bf16_f32 v225, v122, v123
	v_cvt_pk_bf16_f32 v226, v124, v125
	v_cvt_pk_bf16_f32 v227, v126, v127
	v_mfma_f32_32x32x16_bf16 v[16:31], v[200:203], v[108:111], v[16:31]
	v_exp_f32_e32 v80, v80
	v_exp_f32_e32 v81, v81
	v_add_f32_e32 v191, v191, v80
	v_exp_f32_e32 v82, v82
	v_mfma_f32_32x32x16_bf16 v[48:63], v[208:211], v[108:111], v[48:63]
	v_add_f32_e32 v191, v191, v81
	v_exp_f32_e32 v83, v83
	v_add_f32_e32 v191, v191, v82
	v_exp_f32_e32 v84, v84
	v_add_f32_e32 v191, v191, v83
	s_waitcnt lgkmcnt(0)
	s_barrier
	v_mfma_f32_32x32x16_bf16 v[0:15], v[220:223], v[64:67], v[0:15]
	v_exp_f32_e32 v85, v85
	v_add_f32_e32 v191, v191, v84
	v_exp_f32_e32 v86, v86
	v_add_f32_e32 v191, v191, v85
	v_exp_f32_e32 v87, v87
	v_add_f32_e32 v191, v191, v86
	v_mfma_f32_32x32x16_bf16 v[16:31], v[220:223], v[72:75], v[16:31]
	v_exp_f32_e32 v88, v88
	v_add_f32_e32 v191, v191, v87
	v_exp_f32_e32 v89, v89
	v_add_f32_e32 v191, v191, v88
	v_exp_f32_e32 v90, v90
	v_mfma_f32_32x32x16_bf16 v[0:15], v[224:227], v[68:71], v[0:15]
	v_add_f32_e32 v191, v191, v89
	v_exp_f32_e32 v91, v91
	v_add_f32_e32 v191, v191, v90
	v_exp_f32_e32 v92, v92
	v_add_f32_e32 v191, v191, v91
	v_exp_f32_e32 v93, v93
	v_mfma_f32_32x32x16_bf16 v[16:31], v[224:227], v[76:79], v[16:31]
	v_add_f32_e32 v191, v191, v92
	v_exp_f32_e32 v94, v94
	v_add_f32_e32 v191, v191, v93
	v_exp_f32_e32 v95, v95
	v_add_f32_e32 v191, v191, v94
	v_add_f32_e32 v191, v191, v95
	v_cvt_pk_bf16_f32 v228, v80, v81
	v_cvt_pk_bf16_f32 v229, v82, v83
	v_cvt_pk_bf16_f32 v230, v84, v85
	v_cvt_pk_bf16_f32 v231, v86, v87
	v_cvt_pk_bf16_f32 v232, v88, v89
	v_cvt_pk_bf16_f32 v233, v90, v91
	v_cvt_pk_bf16_f32 v234, v92, v93
	v_cvt_pk_bf16_f32 v235, v94, v95
	s_sub_i32 s16, 0x7900, s16
	s_add_i32 s14, s14, -1
	s_cmp_eq_u32 s14, 0
	v_mfma_f32_32x32x16_bf16 v[32:47], v[228:231], v[64:67], v[32:47]
	v_mfma_f32_32x32x16_bf16 v[48:63], v[228:231], v[72:75], v[48:63]
	v_mfma_f32_32x32x16_bf16 v[32:47], v[232:235], v[68:71], v[32:47]
	v_mfma_f32_32x32x16_bf16 v[48:63], v[232:235], v[76:79], v[48:63]
	s_cbranch_scc1 .LBB0_1633
	v_mov_b32_e32 v240, 0x358637bd
	s_branch .LBB0_1629
